# v83 + one static s_setprio 1 for the trailing half (waves 4..7) in every GEMM phase
# baseline (speedup 1.0000x reference)
.LBB0_217:
	s_or_b64 exec, exec, s[4:5]
	s_cmpk_lt_i32 s2, 0x300
	s_cselect_b64 s[6:7], -1, 0
	s_mov_b64 s[4:5], s[0:1]
	s_waitcnt vmcnt(14)
	v_mov_b32_e32 v8, v192
	s_waitcnt lgkmcnt(0)
	s_barrier
	s_load_dwordx2 s[98:99], s[0:1], 0x80
	v_and_b32_e32 v253, 7, v192
	v_lshlrev_b32_e32 v253, 8, v253
	s_waitcnt lgkmcnt(0)
	global_load_dword v254, v253, s[98:99] sc1
	global_load_dword v255, v253, s[98:99] offset:2048 sc1
	s_ashr_i32 s47, s52, 31
	s_ashr_i32 s76, s2, 31
	v_writelane_b32 v250, s6, 0
	v_readfirstlane_b32 s13, v8
	s_and_b64 vcc, exec, s[6:7]
	v_writelane_b32 v250, s7, 1
	s_cbranch_vccz .LBB0_233
	v_lshlrev_b32_e32 v0, 4, v8
	v_add_u32_e32 v1, 0x2000, v0
	v_ashrrev_i32_e32 v2, 31, v1
	v_lshrrev_b32_e32 v2, 22, v2
	v_add_u32_e32 v2, v1, v2
	v_ashrrev_i32_e32 v9, 10, v2
	v_mul_i32_i24_e32 v2, 0x400, v9
	v_sub_u32_e32 v1, v1, v2
	v_lshrrev_b32_e32 v2, 4, v1
	v_bitop3_b32 v1, v2, v1, 32 bitop3:0x6c
	v_ashrrev_i32_e32 v2, 31, v1
	v_lshrrev_b32_e32 v2, 26, v2
	v_add_u32_e32 v2, v1, v2
	v_lshlrev_b32_e32 v3, 3, v9
	s_waitcnt vmcnt(13)
	v_ashrrev_i32_e32 v10, 6, v2
	v_and_b32_e32 v3, -16, v3
	v_add_u32_e32 v3, v10, v3
	v_and_b32_e32 v4, 3, v10
	s_mov_b32 s6, 0xfffe0
	v_lshrrev_b32_e32 v5, 2, v3
	v_lshlrev_b32_e32 v6, 1, v3
	v_and_b32_e32 v2, 0xc0, v2
	v_and_or_b32 v4, v3, s6, v4
	v_and_b32_e32 v5, 4, v5
	v_and_b32_e32 v6, 24, v6
	v_sub_u32_e32 v1, v1, v2
	v_mov_b32_e32 v2, 1
	v_or3_b32 v4, v4, v5, v6
	v_lshlrev_b32_e32 v5, 5, v9
	v_ashrrev_i16_sdwa v1, v2, sext(v1) dst_sel:DWORD dst_unused:UNUSED_PAD src0_sel:DWORD src1_sel:BYTE_0
	v_and_b32_e32 v5, 32, v5
	v_bfe_i32 v11, v1, 0, 16
	v_add_lshl_u32 v1, v5, v11, 1
	v_lshl_add_u32 v128, v4, 12, v1
	v_lshl_add_u32 v130, v3, 12, v1
	v_bfe_i32 v1, v8, 27, 1
	v_lshrrev_b32_e32 v1, 22, v1
	v_add_u32_e32 v1, v0, v1
	v_and_b32_e32 v1, 0xfffffc00, v1
	s_load_dwordx2 s[4:5], s[4:5], 0x80
	v_sub_u32_e32 v0, v0, v1
	v_lshrrev_b32_e32 v1, 4, v0
	v_ashrrev_i32_e32 v3, 31, v8
	v_bitop3_b32 v0, v1, v0, 32 bitop3:0x6c
	v_lshrrev_b32_e32 v3, 26, v3
	v_ashrrev_i32_e32 v1, 31, v0
	v_add_u32_e32 v3, v8, v3
	v_lshrrev_b32_e32 v1, 26, v1
	v_ashrrev_i32_e32 v13, 6, v3
	s_waitcnt lgkmcnt(0)
	s_add_u32 s30, s4, 0xc600000
	v_add_u32_e32 v1, v0, v1
	v_lshlrev_b32_e32 v3, 3, v13
	s_addc_u32 s31, s5, 0
	v_ashrrev_i32_e32 v12, 6, v1
	v_and_b32_e32 v3, -16, v3
	s_add_u32 s34, s4, 0x100000
	v_add_u32_e32 v3, v12, v3
	v_and_b32_e32 v4, 3, v12
	s_addc_u32 s35, s5, 0
	v_and_or_b32 v4, v3, s6, v4
	s_lshr_b32 s6, s76, 29
	s_add_i32 s6, s2, s6
	s_ashr_i32 s10, s13, 6
	s_ashr_i32 s7, s6, 3
	s_and_b32 s6, s6, -8
	s_ashr_i32 s14, s13, 8
	s_lshl_b32 s36, s10, 10
	s_sub_i32 s6, s2, s6
	s_cmp_lt_i32 s6, 0
	s_movk_i32 s37, 0x61
	s_cselect_b32 s8, s37, 0x60
	s_mul_i32 s6, s6, s8
	s_add_i32 s6, s6, s7
	s_mul_hi_i32 s7, s6, 0x2aaaaaab
	s_lshr_b32 s8, s7, 31
	s_ashr_i32 s7, s7, 4
	s_add_i32 s7, s7, s8
	s_lshl_b32 s8, s7, 2
	s_mulk_i32 s7, 0x60
	s_sub_i32 s6, s6, s7
	s_bfe_i32 s7, s6, 0x80000
	s_bfe_u32 s7, s7, 0x2000d
	s_add_i32 s7, s6, s7
	s_bfe_i32 s9, s7, 0x80000
	s_and_b32 s7, s7, 0xfc
	s_sub_i32 s6, s6, s7
	s_sext_i32_i16 s9, s9
	s_sext_i32_i8 s6, s6
	v_lshrrev_b32_e32 v5, 2, v3
	v_lshlrev_b32_e32 v6, 1, v3
	v_and_b32_e32 v1, 0xc0, v1
	s_lshr_b32 s12, s9, 2
	s_add_i32 s22, s8, s6
	v_and_b32_e32 v5, 4, v5
	v_and_b32_e32 v6, 24, v6
	v_sub_u32_e32 v0, v0, v1
	s_ashr_i32 s23, s22, 31
	s_bfe_i64 s[8:9], s[12:13], 0x100000
	v_or3_b32 v4, v4, v5, v6
	v_lshlrev_b32_e32 v5, 5, v13
	v_ashrrev_i16_sdwa v0, v2, sext(v0) dst_sel:DWORD dst_unused:UNUSED_PAD src0_sel:DWORD src1_sel:BYTE_0
	s_lshl_b64 s[6:7], s[22:23], 20
	s_lshl_b64 s[8:9], s[8:9], 20
	v_and_b32_e32 v5, 32, v5
	s_waitcnt vmcnt(12)
	v_bfe_i32 v14, v0, 0, 16
	s_add_u32 s26, s34, s8
	v_add_lshl_u32 v0, v5, v14, 1
	s_addc_u32 s27, s35, s9
	s_add_i32 s23, s36, 0
	v_lshl_add_u32 v132, v4, 12, v0
	s_add_i32 m0, s23, 0x10000
	v_lshl_add_u32 v134, v3, 12, v0
	global_load_lds_dwordx4 v132, s[26:27]
	s_add_i32 m0, s23, 0x12000
	s_add_u32 s8, s26, 0x80000
	global_load_lds_dwordx4 v128, s[26:27]
	s_addc_u32 s9, s27, 0
	s_add_i32 m0, s23, 0x14000
	v_mov_b32_e32 v133, 0
	global_load_lds_dwordx4 v132, s[8:9]
	s_add_i32 m0, s23, 0x16000
	s_add_u32 s24, s30, s6
	s_addc_u32 s25, s31, s7
	s_add_i32 s38, s23, 0x2000
	global_load_lds_dwordx4 v128, s[8:9]
	s_mov_b32 m0, s23
	s_add_u32 s6, s24, 0x80000
	global_load_lds_dwordx4 v134, s[24:25]
	s_mov_b32 m0, s38
	s_addc_u32 s7, s25, 0
	s_add_i32 s39, s23, 0x4000
	global_load_lds_dwordx4 v130, s[24:25]
	s_mov_b32 m0, s39
	s_add_i32 s40, s23, 0x6000
	global_load_lds_dwordx4 v134, s[6:7]
	s_mov_b32 m0, s40
	v_mov_b32_e32 v129, v133
	global_load_lds_dwordx4 v130, s[6:7]
	v_mov_b32_e32 v135, v133
	v_mov_b32_e32 v131, v133
	s_cmp_eq_u32 s14, 1
	s_mov_b32 s41, 0
	v_lshl_add_u64 v[6:7], s[26:27], 0, v[132:133]
	v_lshl_add_u64 v[4:5], s[26:27], 0, v[128:129]
	v_lshl_add_u64 v[0:1], s[24:25], 0, v[134:135]
	s_cselect_b64 s[6:7], -1, 0
	s_cmp_lg_u32 s14, 1
	v_lshl_add_u64 v[2:3], s[24:25], 0, v[130:131]
	s_cbranch_scc1 .LBB0_220
	s_barrier
	s_setprio 1

.LBB0_576:
	s_and_b64 vcc, exec, s[4:5]
	s_cbranch_vccnz .LBB0_612
	v_ashrrev_i32_e32 v1, 31, v8
	v_lshrrev_b32_e32 v1, 26, v1
	v_add_u32_e32 v1, v8, v1
	v_ashrrev_i32_e32 v9, 6, v1
	v_bfe_i32 v1, v8, 27, 1
	v_lshlrev_b32_e32 v0, 4, v8
	v_lshrrev_b32_e32 v1, 22, v1
	v_add_u32_e32 v1, v0, v1
	v_and_b32_e32 v1, 0xfffffc00, v1
	v_sub_u32_e32 v1, v0, v1
	v_lshrrev_b32_e32 v2, 4, v1
	v_bitop3_b32 v1, v2, v1, 32 bitop3:0x6c
	v_ashrrev_i32_e32 v3, 31, v1
	v_lshrrev_b32_e32 v3, 26, v3
	v_add_u32_e32 v3, v1, v3
	v_lshlrev_b32_e32 v2, 3, v9
	v_ashrrev_i32_e32 v10, 6, v3
	v_and_b32_e32 v3, 0xc0, v3
	v_and_b32_e32 v2, -16, v2
	v_sub_u32_e32 v1, v1, v3
	v_mov_b32_e32 v3, 1
	v_add_u32_e32 v2, v10, v2
	v_ashrrev_i16_sdwa v1, v3, sext(v1) dst_sel:DWORD dst_unused:UNUSED_PAD src0_sel:DWORD src1_sel:BYTE_0
	v_lshlrev_b32_e32 v4, 5, v9
	v_bfe_i32 v11, v1, 0, 16
	v_lshlrev_b32_e32 v1, 1, v2
	v_lshrrev_b32_e32 v5, 2, v2
	v_and_b32_e32 v6, 3, v10
	s_mov_b32 s9, 0xfffe0
	v_and_b32_e32 v4, 32, v4
	v_and_b32_e32 v1, 24, v1
	v_and_b32_e32 v5, 4, v5
	v_and_or_b32 v6, v2, s9, v6
	v_or3_b32 v1, v6, v5, v1
	v_add_lshl_u32 v4, v4, v11, 1
	v_add_u32_e32 v0, 0x2000, v0
	v_lshl_add_u32 v130, v1, 12, v4
	v_ashrrev_i32_e32 v1, 31, v0
	v_lshrrev_b32_e32 v1, 22, v1
	v_add_u32_e32 v1, v0, v1
	v_ashrrev_i32_e32 v12, 10, v1
	v_mul_i32_i24_e32 v1, 0x400, v12
	v_sub_u32_e32 v0, v0, v1
	v_lshrrev_b32_e32 v1, 4, v0
	v_bitop3_b32 v0, v1, v0, 32 bitop3:0x6c
	v_lshl_add_u32 v128, v2, 12, v4
	v_ashrrev_i32_e32 v2, 31, v0
	v_lshrrev_b32_e32 v2, 26, v2
	v_add_u32_e32 v2, v0, v2
	s_waitcnt lgkmcnt(0)
	s_add_u32 s60, s6, 0xc600000
	v_lshlrev_b32_e32 v1, 3, v12
	v_ashrrev_i32_e32 v13, 6, v2
	v_and_b32_e32 v2, 0xc0, v2
	s_addc_u32 s61, s7, 0
	v_and_b32_e32 v1, -16, v1
	v_sub_u32_e32 v0, v0, v2
	s_add_u32 s62, s6, 0x1a00000
	v_add_u32_e32 v1, v13, v1
	v_ashrrev_i16_sdwa v0, v3, sext(v0) dst_sel:DWORD dst_unused:UNUSED_PAD src0_sel:DWORD src1_sel:BYTE_0
	v_and_b32_e32 v3, 3, v13
	s_addc_u32 s63, s7, 0
	v_and_or_b32 v3, v1, s9, v3
	s_ashr_i32 s9, s20, 6
	s_ashr_i32 s41, s40, 31
	s_ashr_i32 s43, s42, 31
	s_ashr_i32 s8, s20, 8
	s_lshl_b32 s64, s9, 10
	s_lshl_b64 s[12:13], s[40:41], 20
	s_lshl_b64 s[14:15], s[42:43], 20
	s_add_u32 s50, s62, s14
	v_lshlrev_b32_e32 v4, 5, v12
	v_bfe_i32 v14, v0, 0, 16
	v_lshlrev_b32_e32 v0, 1, v1
	v_lshrrev_b32_e32 v2, 2, v1
	s_addc_u32 s51, s63, s15
	s_add_i32 s43, s64, 0
	v_and_b32_e32 v4, 32, v4
	v_and_b32_e32 v0, 24, v0
	v_and_b32_e32 v2, 4, v2
	s_add_i32 m0, s43, 0x10000
	v_or3_b32 v0, v3, v2, v0
	v_add_lshl_u32 v2, v4, v14, 1
	global_load_lds_dwordx4 v130, s[50:51]
	s_add_i32 m0, s43, 0x12000
	v_lshl_add_u32 v134, v0, 12, v2
	s_add_u32 s14, s50, 0x80000
	global_load_lds_dwordx4 v134, s[50:51]
	s_addc_u32 s15, s51, 0
	s_add_i32 m0, s43, 0x14000
	v_lshl_add_u32 v132, v1, 12, v2
	global_load_lds_dwordx4 v130, s[14:15]
	s_add_i32 m0, s43, 0x16000
	s_add_u32 s48, s60, s12
	s_addc_u32 s49, s61, s13
	s_add_i32 s65, s43, 0x2000
	global_load_lds_dwordx4 v134, s[14:15]
	s_mov_b32 m0, s43
	s_add_u32 s12, s48, 0x80000
	global_load_lds_dwordx4 v128, s[48:49]
	s_mov_b32 m0, s65
	s_addc_u32 s13, s49, 0
	s_add_i32 s66, s43, 0x4000
	global_load_lds_dwordx4 v132, s[48:49]
	s_mov_b32 m0, s66
	s_add_i32 s67, s43, 0x6000
	global_load_lds_dwordx4 v128, s[12:13]
	s_mov_b32 m0, s67
	v_mov_b32_e32 v131, 0
	global_load_lds_dwordx4 v132, s[12:13]
	v_mov_b32_e32 v135, v131
	v_mov_b32_e32 v129, v131
	v_mov_b32_e32 v133, v131
	s_cmp_eq_u32 s8, 1
	s_mov_b32 s68, 0
	v_lshl_add_u64 v[6:7], s[50:51], 0, v[130:131]
	v_lshl_add_u64 v[4:5], s[50:51], 0, v[134:135]
	v_lshl_add_u64 v[0:1], s[48:49], 0, v[128:129]
	s_cselect_b64 s[12:13], -1, 0
	s_cmp_lg_u32 s8, 1
	v_lshl_add_u64 v[2:3], s[48:49], 0, v[132:133]
	s_cbranch_scc1 .LBB0_579
	s_barrier
	s_setprio 1

.LBB0_664:
	s_or_b64 exec, exec, s[6:7]
	s_cmpk_lt_i32 s2, 0x580
	s_cselect_b64 s[14:15], -1, 0
	s_mov_b64 s[6:7], s[0:1]
	v_mov_b32_e32 v8, v192
	s_waitcnt lgkmcnt(0)
	s_barrier
	s_and_b64 vcc, exec, s[14:15]
	v_readfirstlane_b32 s21, v8
	s_cbranch_vccz .LBB0_680
	v_lshlrev_b32_e32 v0, 4, v8
	v_add_u32_e32 v1, 0x2000, v0
	v_ashrrev_i32_e32 v2, 31, v1
	v_lshrrev_b32_e32 v2, 22, v2
	v_add_u32_e32 v2, v1, v2
	v_ashrrev_i32_e32 v9, 10, v2
	v_mul_i32_i24_e32 v2, 0x400, v9
	v_sub_u32_e32 v1, v1, v2
	v_lshrrev_b32_e32 v2, 4, v1
	v_bitop3_b32 v1, v2, v1, 32 bitop3:0x6c
	v_ashrrev_i32_e32 v2, 31, v1
	v_lshrrev_b32_e32 v2, 26, v2
	v_add_u32_e32 v2, v1, v2
	v_lshlrev_b32_e32 v3, 3, v9
	v_ashrrev_i32_e32 v10, 6, v2
	v_and_b32_e32 v3, -16, v3
	v_add_u32_e32 v3, v10, v3
	v_and_b32_e32 v4, 3, v10
	s_mov_b32 s8, 0xfffe0
	v_lshrrev_b32_e32 v5, 2, v3
	v_lshlrev_b32_e32 v6, 1, v3
	v_and_b32_e32 v2, 0xc0, v2
	v_and_or_b32 v4, v3, s8, v4
	v_and_b32_e32 v5, 4, v5
	v_and_b32_e32 v6, 24, v6
	v_sub_u32_e32 v1, v1, v2
	v_mov_b32_e32 v2, 1
	v_or3_b32 v4, v4, v5, v6
	v_lshlrev_b32_e32 v5, 5, v9
	v_ashrrev_i16_sdwa v1, v2, sext(v1) dst_sel:DWORD dst_unused:UNUSED_PAD src0_sel:DWORD src1_sel:BYTE_0
	v_and_b32_e32 v5, 32, v5
	v_bfe_i32 v11, v1, 0, 16
	v_add_lshl_u32 v1, v5, v11, 1
	v_lshl_add_u32 v128, v4, 12, v1
	v_lshl_add_u32 v130, v3, 12, v1
	v_bfe_i32 v1, v8, 27, 1
	v_lshrrev_b32_e32 v1, 22, v1
	v_add_u32_e32 v1, v0, v1
	v_and_b32_e32 v1, 0xfffffc00, v1
	s_load_dwordx2 s[6:7], s[6:7], 0x80
	v_sub_u32_e32 v0, v0, v1
	v_lshrrev_b32_e32 v1, 4, v0
	v_ashrrev_i32_e32 v3, 31, v8
	v_bitop3_b32 v0, v1, v0, 32 bitop3:0x6c
	v_lshrrev_b32_e32 v3, 26, v3
	v_ashrrev_i32_e32 v1, 31, v0
	v_add_u32_e32 v3, v8, v3
	v_lshrrev_b32_e32 v1, 26, v1
	v_ashrrev_i32_e32 v13, 6, v3
	s_waitcnt lgkmcnt(0)
	s_add_u32 s38, s6, 0x27000000
	v_add_u32_e32 v1, v0, v1
	v_lshlrev_b32_e32 v3, 3, v13
	s_addc_u32 s39, s7, 0
	v_ashrrev_i32_e32 v12, 6, v1
	v_and_b32_e32 v3, -16, v3
	s_add_u32 s40, s6, 0x2200000
	v_add_u32_e32 v3, v12, v3
	v_and_b32_e32 v4, 3, v12
	s_addc_u32 s41, s7, 0
	v_and_or_b32 v4, v3, s8, v4
	s_lshr_b32 s8, s76, 29
	s_add_i32 s8, s2, s8
	s_ashr_i32 s18, s21, 6
	s_ashr_i32 s9, s8, 3
	s_and_b32 s8, s8, -8
	s_ashr_i32 s22, s21, 8
	s_lshl_b32 s42, s18, 10
	s_sub_i32 s8, s2, s8
	s_cmp_lt_i32 s8, 0
	s_movk_i32 s43, 0xb1
	s_cselect_b32 s10, s43, 0xb0
	s_mul_i32 s8, s8, s10
	s_add_i32 s8, s8, s9
	s_mul_hi_i32 s9, s8, 0x2e8ba2e9
	s_lshr_b32 s10, s9, 31
	s_ashr_i32 s9, s9, 5
	s_add_i32 s9, s9, s10
	s_lshl_b32 s10, s9, 2
	s_mulk_i32 s9, 0xb0
	s_sub_i32 s8, s8, s9
	s_sext_i32_i16 s9, s8
	s_bfe_u32 s9, s9, 0x2001d
	s_add_i32 s9, s8, s9
	s_sext_i32_i16 s11, s9
	s_and_b32 s9, s9, 0xfffc
	s_sub_i32 s8, s8, s9
	s_sext_i32_i16 s8, s8
	v_lshrrev_b32_e32 v5, 2, v3
	v_lshlrev_b32_e32 v6, 1, v3
	v_and_b32_e32 v1, 0xc0, v1
	s_lshr_b32 s20, s11, 2
	s_add_i32 s8, s10, s8
	v_and_b32_e32 v5, 4, v5
	v_and_b32_e32 v6, 24, v6
	v_sub_u32_e32 v0, v0, v1
	s_ashr_i32 s9, s8, 31
	s_bfe_i64 s[12:13], s[20:21], 0x100000
	v_or3_b32 v4, v4, v5, v6
	v_lshlrev_b32_e32 v5, 5, v13
	v_ashrrev_i16_sdwa v0, v2, sext(v0) dst_sel:DWORD dst_unused:UNUSED_PAD src0_sel:DWORD src1_sel:BYTE_0
	s_lshl_b64 s[10:11], s[8:9], 20
	s_lshl_b64 s[12:13], s[12:13], 20
	v_and_b32_e32 v5, 32, v5
	v_bfe_i32 v14, v0, 0, 16
	s_add_u32 s34, s40, s12
	v_add_lshl_u32 v0, v5, v14, 1
	s_addc_u32 s35, s41, s13
	s_add_i32 s48, s42, 0
	v_lshl_add_u32 v132, v4, 12, v0
	s_add_i32 m0, s48, 0x10000
	v_lshl_add_u32 v134, v3, 12, v0
	global_load_lds_dwordx4 v132, s[34:35]
	s_add_i32 m0, s48, 0x12000
	s_add_u32 s12, s34, 0x80000
	global_load_lds_dwordx4 v128, s[34:35]
	s_addc_u32 s13, s35, 0
	s_add_i32 m0, s48, 0x14000
	v_mov_b32_e32 v133, 0
	global_load_lds_dwordx4 v132, s[12:13]
	s_add_i32 m0, s48, 0x16000
	s_add_u32 s30, s38, s10
	s_addc_u32 s31, s39, s11
	s_add_i32 s49, s48, 0x2000
	global_load_lds_dwordx4 v128, s[12:13]
	s_mov_b32 m0, s48
	s_add_u32 s10, s30, 0x80000
	global_load_lds_dwordx4 v134, s[30:31]
	s_mov_b32 m0, s49
	s_addc_u32 s11, s31, 0
	s_add_i32 s50, s48, 0x4000
	global_load_lds_dwordx4 v130, s[30:31]
	s_mov_b32 m0, s50
	s_add_i32 s51, s48, 0x6000
	global_load_lds_dwordx4 v134, s[10:11]
	s_mov_b32 m0, s51
	v_mov_b32_e32 v129, v133
	global_load_lds_dwordx4 v130, s[10:11]
	v_mov_b32_e32 v135, v133
	v_mov_b32_e32 v131, v133
	s_cmp_eq_u32 s22, 1
	s_mov_b32 s58, 0
	v_lshl_add_u64 v[6:7], s[34:35], 0, v[132:133]
	v_lshl_add_u64 v[4:5], s[34:35], 0, v[128:129]
	v_lshl_add_u64 v[0:1], s[30:31], 0, v[134:135]
	s_cselect_b64 s[10:11], -1, 0
	s_cmp_lg_u32 s22, 1
	v_lshl_add_u64 v[2:3], s[30:31], 0, v[130:131]
	s_cbranch_scc1 .LBB0_667
	s_barrier
	s_setprio 1

.LBB0_1170:
	s_and_b64 vcc, exec, s[4:5]
	s_cbranch_vccnz .LBB0_1210
	v_ashrrev_i32_e32 v1, 31, v8
	v_lshrrev_b32_e32 v1, 26, v1
	v_add_u32_e32 v1, v8, v1
	v_ashrrev_i32_e32 v9, 6, v1
	v_bfe_i32 v1, v8, 27, 1
	v_lshlrev_b32_e32 v0, 4, v8
	v_lshrrev_b32_e32 v1, 22, v1
	v_add_u32_e32 v1, v0, v1
	v_and_b32_e32 v1, 0xfffffc00, v1
	v_sub_u32_e32 v1, v0, v1
	v_lshrrev_b32_e32 v2, 4, v1
	v_bitop3_b32 v1, v2, v1, 32 bitop3:0x6c
	v_ashrrev_i32_e32 v3, 31, v1
	v_lshrrev_b32_e32 v3, 26, v3
	v_lshlrev_b32_e32 v2, 3, v9
	v_add_u32_e32 v3, v1, v3
	v_and_b32_e32 v2, -16, v2
	v_ashrrev_i32_e32 v10, 6, v3
	v_and_b32_e32 v3, 0xc0, v3
	v_add_u32_e32 v2, v10, v2
	v_lshlrev_b32_e32 v4, 5, v9
	v_sub_u32_e32 v1, v1, v3
	v_mov_b32_e32 v3, 1
	v_and_b32_e32 v11, 32, v4
	v_ashrrev_i16_sdwa v1, v3, sext(v1) dst_sel:DWORD dst_unused:UNUSED_PAD src0_sel:DWORD src1_sel:BYTE_0
	v_lshlrev_b32_e32 v4, 1, v2
	v_lshrrev_b32_e32 v5, 2, v2
	v_and_b32_e32 v6, 3, v10
	s_mov_b32 s11, 0x7fffe0
	s_waitcnt vmcnt(14)
	v_bfe_i32 v12, v1, 0, 16
	v_and_b32_e32 v4, 24, v4
	v_and_b32_e32 v5, 4, v5
	v_and_or_b32 v6, v2, s11, v6
	s_movk_i32 s9, 0x1600
	v_add_u32_e32 v1, v11, v12
	v_or3_b32 v4, v6, v5, v4
	v_mul_lo_u32 v2, v2, s9
	v_add_lshl_u32 v128, v1, v2, 1
	v_mul_u32_u24_e32 v2, 0x1600, v4
	v_add_u32_e32 v0, 0x2000, v0
	v_add_lshl_u32 v130, v2, v1, 1
	v_ashrrev_i32_e32 v1, 31, v0
	v_lshrrev_b32_e32 v1, 22, v1
	v_add_u32_e32 v1, v0, v1
	v_ashrrev_i32_e32 v13, 10, v1
	v_mul_i32_i24_e32 v1, 0x400, v13
	v_sub_u32_e32 v0, v0, v1
	v_lshrrev_b32_e32 v1, 4, v0
	v_bitop3_b32 v0, v1, v0, 32 bitop3:0x6c
	v_ashrrev_i32_e32 v2, 31, v0
	v_lshrrev_b32_e32 v2, 26, v2
	s_waitcnt lgkmcnt(0)
	s_add_u32 s38, s6, 0x21800000
	v_lshlrev_b32_e32 v1, 3, v13
	v_add_u32_e32 v2, v0, v2
	s_addc_u32 s39, s7, 0
	v_and_b32_e32 v1, -16, v1
	v_ashrrev_i32_e32 v14, 6, v2
	v_lshlrev_b32_e32 v4, 5, v13
	s_add_u32 s40, s6, 0x4e00000
	v_add_u32_e32 v1, v14, v1
	v_and_b32_e32 v15, 32, v4
	v_and_b32_e32 v4, 3, v14
	s_addc_u32 s41, s7, 0
	v_and_b32_e32 v2, 0xc0, v2
	v_and_or_b32 v4, v1, s11, v4
	s_ashr_i32 s11, s10, 6
	s_ashr_i32 s8, s10, 8
	v_sub_u32_e32 v0, v0, v2
	s_lshl_b32 s42, s11, 10
	s_mul_i32 s13, s65, 0x2c0000
	v_ashrrev_i16_sdwa v0, v3, sext(v0) dst_sel:DWORD dst_unused:UNUSED_PAD src0_sel:DWORD src1_sel:BYTE_0
	v_lshlrev_b32_e32 v2, 1, v1
	v_lshrrev_b32_e32 v3, 2, v1
	s_mul_hi_i32 s12, s65, 0x2c0000
	s_add_u32 s30, s40, s13
	s_waitcnt vmcnt(13)
	v_bfe_i32 v16, v0, 0, 16
	v_and_b32_e32 v2, 24, v2
	v_and_b32_e32 v3, 4, v3
	s_addc_u32 s31, s41, s12
	s_add_i32 s43, s42, 0
	v_add_u32_e32 v0, v15, v16
	v_or3_b32 v2, v4, v3, v2
	v_mul_lo_u32 v1, v1, s9
	s_add_i32 m0, s43, 0x10000
	v_add_lshl_u32 v132, v0, v1, 1
	v_mul_u32_u24_e32 v1, 0x1600, v2
	global_load_lds_dwordx4 v130, s[30:31]
	s_add_i32 m0, s43, 0x12000
	v_add_lshl_u32 v134, v1, v0, 1
	s_add_u32 s12, s30, 0x160000
	global_load_lds_dwordx4 v134, s[30:31]
	s_addc_u32 s13, s31, 0
	s_add_i32 m0, s43, 0x14000
	s_mul_i32 s17, s64, 0x2c0000
	global_load_lds_dwordx4 v130, s[12:13]
	s_add_i32 m0, s43, 0x16000
	s_mul_hi_i32 s16, s64, 0x2c0000
	s_add_u32 s28, s38, s17
	s_addc_u32 s29, s39, s16
	s_add_i32 s48, s43, 0x2000
	global_load_lds_dwordx4 v134, s[12:13]
	s_mov_b32 m0, s43
	s_add_u32 s12, s28, 0x160000
	global_load_lds_dwordx4 v128, s[28:29]
	s_mov_b32 m0, s48
	s_addc_u32 s13, s29, 0
	s_add_i32 s49, s43, 0x4000
	global_load_lds_dwordx4 v132, s[28:29]
	s_mov_b32 m0, s49
	s_add_i32 s50, s43, 0x6000
	global_load_lds_dwordx4 v128, s[12:13]
	s_mov_b32 m0, s50
	v_mov_b32_e32 v131, 0
	global_load_lds_dwordx4 v132, s[12:13]
	v_mov_b32_e32 v135, v131
	v_mov_b32_e32 v129, v131
	v_mov_b32_e32 v133, v131
	s_cmp_eq_u32 s8, 1
	s_mov_b32 s51, 0
	v_lshl_add_u64 v[6:7], s[30:31], 0, v[130:131]
	v_lshl_add_u64 v[2:3], s[30:31], 0, v[134:135]
	s_mov_b32 s26, 0x16000
	v_lshl_add_u64 v[0:1], s[28:29], 0, v[128:129]
	s_cselect_b64 s[12:13], -1, 0
	s_cmp_lg_u32 s8, 1
	v_lshl_add_u64 v[4:5], s[28:29], 0, v[132:133]
	s_cbranch_scc1 .LBB0_1173
	s_barrier
	s_setprio 1

.LBB0_1262:
	s_or_b64 exec, exec, s[6:7]
	v_readlane_b32 s8, v250, 0
	s_mov_b64 s[6:7], s[0:1]
	v_mov_b32_e32 v8, v192
	v_readlane_b32 s9, v250, 1
	s_waitcnt lgkmcnt(0)
	s_barrier
	s_andn2_b64 vcc, exec, s[8:9]
	v_readfirstlane_b32 s21, v8
	s_cbranch_vccnz .LBB0_1278
	v_lshlrev_b32_e32 v0, 4, v8
	v_add_u32_e32 v1, 0x2000, v0
	v_ashrrev_i32_e32 v2, 31, v1
	v_lshrrev_b32_e32 v2, 22, v2
	v_add_u32_e32 v2, v1, v2
	v_ashrrev_i32_e32 v9, 10, v2
	v_mul_i32_i24_e32 v2, 0x400, v9
	v_sub_u32_e32 v1, v1, v2
	v_lshrrev_b32_e32 v2, 4, v1
	v_bitop3_b32 v1, v2, v1, 32 bitop3:0x6c
	v_ashrrev_i32_e32 v2, 31, v1
	v_lshrrev_b32_e32 v2, 26, v2
	v_add_u32_e32 v2, v1, v2
	v_lshlrev_b32_e32 v3, 3, v9
	v_ashrrev_i32_e32 v10, 6, v2
	v_and_b32_e32 v3, -16, v3
	v_add_u32_e32 v3, v10, v3
	v_and_b32_e32 v4, 3, v10
	s_mov_b32 s8, 0xfffe0
	v_lshrrev_b32_e32 v5, 2, v3
	v_lshlrev_b32_e32 v6, 1, v3
	v_and_b32_e32 v2, 0xc0, v2
	v_and_or_b32 v4, v3, s8, v4
	v_and_b32_e32 v5, 4, v5
	v_and_b32_e32 v6, 24, v6
	v_sub_u32_e32 v1, v1, v2
	v_mov_b32_e32 v2, 1
	v_or3_b32 v4, v4, v5, v6
	v_lshlrev_b32_e32 v5, 5, v9
	v_ashrrev_i16_sdwa v1, v2, sext(v1) dst_sel:DWORD dst_unused:UNUSED_PAD src0_sel:DWORD src1_sel:BYTE_0
	v_and_b32_e32 v5, 32, v5
	v_bfe_i32 v11, v1, 0, 16
	v_add_lshl_u32 v1, v5, v11, 1
	v_lshl_add_u32 v128, v4, 12, v1
	v_lshl_add_u32 v130, v3, 12, v1
	v_bfe_i32 v1, v8, 27, 1
	v_lshrrev_b32_e32 v1, 22, v1
	v_add_u32_e32 v1, v0, v1
	v_and_b32_e32 v1, 0xfffffc00, v1
	s_load_dwordx2 s[6:7], s[6:7], 0x80
	v_sub_u32_e32 v0, v0, v1
	v_lshrrev_b32_e32 v1, 4, v0
	v_ashrrev_i32_e32 v3, 31, v8
	v_bitop3_b32 v0, v1, v0, 32 bitop3:0x6c
	v_lshrrev_b32_e32 v3, 26, v3
	v_ashrrev_i32_e32 v1, 31, v0
	v_add_u32_e32 v3, v8, v3
	v_lshrrev_b32_e32 v1, 26, v1
	s_waitcnt vmcnt(14)
	v_ashrrev_i32_e32 v13, 6, v3
	s_waitcnt lgkmcnt(0)
	s_add_u32 s38, s6, 0xc600000
	v_add_u32_e32 v1, v0, v1
	v_lshlrev_b32_e32 v3, 3, v13
	s_addc_u32 s39, s7, 0
	v_ashrrev_i32_e32 v12, 6, v1
	v_and_b32_e32 v3, -16, v3
	s_add_u32 s40, s6, 0x6400000
	v_add_u32_e32 v3, v12, v3
	v_and_b32_e32 v4, 3, v12
	s_addc_u32 s41, s7, 0
	v_and_or_b32 v4, v3, s8, v4
	s_lshr_b32 s8, s76, 29
	s_add_i32 s8, s2, s8
	s_ashr_i32 s18, s21, 6
	s_ashr_i32 s9, s8, 3
	s_and_b32 s8, s8, -8
	s_ashr_i32 s22, s21, 8
	s_lshl_b32 s42, s18, 10
	s_sub_i32 s8, s2, s8
	s_cmp_lt_i32 s8, 0
	s_movk_i32 s43, 0x61
	s_cselect_b32 s10, s43, 0x60
	s_mul_i32 s8, s8, s10
	s_add_i32 s8, s8, s9
	s_mul_hi_i32 s9, s8, 0x2aaaaaab
	s_lshr_b32 s10, s9, 31
	s_ashr_i32 s9, s9, 4
	s_add_i32 s9, s9, s10
	s_lshl_b32 s10, s9, 2
	s_mulk_i32 s9, 0x60
	s_sub_i32 s8, s8, s9
	s_bfe_i32 s9, s8, 0x80000
	s_bfe_u32 s9, s9, 0x2000d
	s_add_i32 s9, s8, s9
	s_bfe_i32 s11, s9, 0x80000
	s_and_b32 s9, s9, 0xfc
	s_sub_i32 s8, s8, s9
	s_sext_i32_i16 s11, s11
	s_sext_i32_i8 s8, s8
	v_lshrrev_b32_e32 v5, 2, v3
	v_lshlrev_b32_e32 v6, 1, v3
	v_and_b32_e32 v1, 0xc0, v1
	s_lshr_b32 s20, s11, 2
	s_add_i32 s8, s10, s8
	v_and_b32_e32 v5, 4, v5
	v_and_b32_e32 v6, 24, v6
	v_sub_u32_e32 v0, v0, v1
	s_ashr_i32 s9, s8, 31
	s_bfe_i64 s[12:13], s[20:21], 0x100000
	v_or3_b32 v4, v4, v5, v6
	v_lshlrev_b32_e32 v5, 5, v13
	v_ashrrev_i16_sdwa v0, v2, sext(v0) dst_sel:DWORD dst_unused:UNUSED_PAD src0_sel:DWORD src1_sel:BYTE_0
	s_lshl_b64 s[10:11], s[8:9], 20
	s_lshl_b64 s[12:13], s[12:13], 20
	v_and_b32_e32 v5, 32, v5
	v_bfe_i32 v14, v0, 0, 16
	s_add_u32 s34, s40, s12
	v_add_lshl_u32 v0, v5, v14, 1
	s_addc_u32 s35, s41, s13
	s_add_i32 s48, s42, 0
	v_lshl_add_u32 v132, v4, 12, v0
	s_add_i32 m0, s48, 0x10000
	v_lshl_add_u32 v134, v3, 12, v0
	global_load_lds_dwordx4 v132, s[34:35]
	s_add_i32 m0, s48, 0x12000
	s_add_u32 s12, s34, 0x80000
	global_load_lds_dwordx4 v128, s[34:35]
	s_addc_u32 s13, s35, 0
	s_add_i32 m0, s48, 0x14000
	v_mov_b32_e32 v133, 0
	global_load_lds_dwordx4 v132, s[12:13]
	s_add_i32 m0, s48, 0x16000
	s_add_u32 s30, s38, s10
	s_addc_u32 s31, s39, s11
	s_add_i32 s49, s48, 0x2000
	global_load_lds_dwordx4 v128, s[12:13]
	s_mov_b32 m0, s48
	s_add_u32 s10, s30, 0x80000
	global_load_lds_dwordx4 v134, s[30:31]
	s_mov_b32 m0, s49
	s_addc_u32 s11, s31, 0
	s_add_i32 s50, s48, 0x4000
	global_load_lds_dwordx4 v130, s[30:31]
	s_mov_b32 m0, s50
	s_add_i32 s51, s48, 0x6000
	global_load_lds_dwordx4 v134, s[10:11]
	s_mov_b32 m0, s51
	v_mov_b32_e32 v129, v133
	global_load_lds_dwordx4 v130, s[10:11]
	v_mov_b32_e32 v135, v133
	v_mov_b32_e32 v131, v133
	s_cmp_eq_u32 s22, 1
	s_mov_b32 s56, 0
	v_lshl_add_u64 v[6:7], s[34:35], 0, v[132:133]
	v_lshl_add_u64 v[4:5], s[34:35], 0, v[128:129]
	v_lshl_add_u64 v[0:1], s[30:31], 0, v[134:135]
	s_cselect_b64 s[10:11], -1, 0
	s_cmp_lg_u32 s22, 1
	v_lshl_add_u64 v[2:3], s[30:31], 0, v[130:131]
	s_cbranch_scc1 .LBB0_1265
	s_barrier
	s_setprio 1

.LBB0_1407:
	s_and_b64 vcc, exec, s[4:5]
	s_cbranch_vccnz .LBB0_1443
	v_ashrrev_i32_e32 v1, 31, v8
	v_lshrrev_b32_e32 v1, 26, v1
	v_add_u32_e32 v1, v8, v1
	v_ashrrev_i32_e32 v9, 6, v1
	v_bfe_i32 v1, v8, 27, 1
	v_lshlrev_b32_e32 v0, 4, v8
	v_lshrrev_b32_e32 v1, 22, v1
	v_add_u32_e32 v1, v0, v1
	v_and_b32_e32 v1, 0xfffffc00, v1
	v_sub_u32_e32 v1, v0, v1
	v_lshrrev_b32_e32 v2, 4, v1
	v_bitop3_b32 v1, v2, v1, 32 bitop3:0x6c
	v_ashrrev_i32_e32 v3, 31, v1
	v_lshrrev_b32_e32 v3, 26, v3
	v_add_u32_e32 v3, v1, v3
	v_lshlrev_b32_e32 v2, 3, v9
	v_ashrrev_i32_e32 v10, 6, v3
	v_and_b32_e32 v3, 0xc0, v3
	v_and_b32_e32 v2, -16, v2
	v_sub_u32_e32 v1, v1, v3
	v_mov_b32_e32 v3, 1
	v_add_u32_e32 v2, v10, v2
	v_ashrrev_i16_sdwa v1, v3, sext(v1) dst_sel:DWORD dst_unused:UNUSED_PAD src0_sel:DWORD src1_sel:BYTE_0
	v_lshlrev_b32_e32 v4, 5, v9
	v_bfe_i32 v11, v1, 0, 16
	v_lshlrev_b32_e32 v1, 1, v2
	v_lshrrev_b32_e32 v5, 2, v2
	v_and_b32_e32 v6, 3, v10
	s_mov_b32 s9, 0xfffe0
	v_and_b32_e32 v4, 32, v4
	v_and_b32_e32 v1, 24, v1
	v_and_b32_e32 v5, 4, v5
	v_and_or_b32 v6, v2, s9, v6
	v_or3_b32 v1, v6, v5, v1
	v_add_lshl_u32 v4, v4, v11, 1
	v_add_u32_e32 v0, 0x2000, v0
	s_waitcnt vmcnt(15)
	v_lshl_add_u32 v130, v1, 12, v4
	v_ashrrev_i32_e32 v1, 31, v0
	v_lshrrev_b32_e32 v1, 22, v1
	v_add_u32_e32 v1, v0, v1
	s_waitcnt vmcnt(14)
	v_ashrrev_i32_e32 v12, 10, v1
	v_mul_i32_i24_e32 v1, 0x400, v12
	v_sub_u32_e32 v0, v0, v1
	v_lshrrev_b32_e32 v1, 4, v0
	v_bitop3_b32 v0, v1, v0, 32 bitop3:0x6c
	v_lshl_add_u32 v128, v2, 12, v4
	v_ashrrev_i32_e32 v2, 31, v0
	v_lshrrev_b32_e32 v2, 26, v2
	v_add_u32_e32 v2, v0, v2
	s_waitcnt lgkmcnt(0)
	s_add_u32 s48, s6, 0x19800000
	v_lshlrev_b32_e32 v1, 3, v12
	v_ashrrev_i32_e32 v13, 6, v2
	v_and_b32_e32 v2, 0xc0, v2
	s_addc_u32 s49, s7, 0
	v_and_b32_e32 v1, -16, v1
	v_sub_u32_e32 v0, v0, v2
	s_add_u32 s50, s6, 0x7c00000
	v_add_u32_e32 v1, v13, v1
	v_ashrrev_i16_sdwa v0, v3, sext(v0) dst_sel:DWORD dst_unused:UNUSED_PAD src0_sel:DWORD src1_sel:BYTE_0
	v_and_b32_e32 v3, 3, v13
	s_addc_u32 s51, s7, 0
	v_and_or_b32 v3, v1, s9, v3
	s_ashr_i32 s9, s22, 6
	s_ashr_i32 s35, s34, 31
	s_ashr_i32 s37, s36, 31
	s_ashr_i32 s8, s22, 8
	s_lshl_b32 s56, s9, 10
	s_lshl_b64 s[10:11], s[34:35], 20
	s_lshl_b64 s[12:13], s[36:37], 20
	s_add_u32 s40, s50, s12
	v_lshlrev_b32_e32 v4, 5, v12
	v_bfe_i32 v14, v0, 0, 16
	v_lshlrev_b32_e32 v0, 1, v1
	v_lshrrev_b32_e32 v2, 2, v1
	s_addc_u32 s41, s51, s13
	s_add_i32 s37, s56, 0
	v_and_b32_e32 v4, 32, v4
	v_and_b32_e32 v0, 24, v0
	v_and_b32_e32 v2, 4, v2
	s_add_i32 m0, s37, 0x10000
	v_or3_b32 v0, v3, v2, v0
	v_add_lshl_u32 v2, v4, v14, 1
	global_load_lds_dwordx4 v130, s[40:41]
	s_add_i32 m0, s37, 0x12000
	v_lshl_add_u32 v134, v0, 12, v2
	s_add_u32 s12, s40, 0x80000
	global_load_lds_dwordx4 v134, s[40:41]
	s_addc_u32 s13, s41, 0
	s_add_i32 m0, s37, 0x14000
	v_lshl_add_u32 v132, v1, 12, v2
	global_load_lds_dwordx4 v130, s[12:13]
	s_add_i32 m0, s37, 0x16000
	s_add_u32 s38, s48, s10
	s_addc_u32 s39, s49, s11
	s_add_i32 s57, s37, 0x2000
	global_load_lds_dwordx4 v134, s[12:13]
	s_mov_b32 m0, s37
	s_add_u32 s10, s38, 0x80000
	global_load_lds_dwordx4 v128, s[38:39]
	s_mov_b32 m0, s57
	s_addc_u32 s11, s39, 0
	s_add_i32 s58, s37, 0x4000
	global_load_lds_dwordx4 v132, s[38:39]
	s_mov_b32 m0, s58
	s_add_i32 s59, s37, 0x6000
	global_load_lds_dwordx4 v128, s[10:11]
	s_mov_b32 m0, s59
	v_mov_b32_e32 v131, 0
	global_load_lds_dwordx4 v132, s[10:11]
	v_mov_b32_e32 v135, v131
	v_mov_b32_e32 v129, v131
	v_mov_b32_e32 v133, v131
	s_cmp_eq_u32 s8, 1
	s_mov_b32 s60, 0
	v_lshl_add_u64 v[6:7], s[40:41], 0, v[130:131]
	v_lshl_add_u64 v[4:5], s[40:41], 0, v[134:135]
	v_lshl_add_u64 v[0:1], s[38:39], 0, v[128:129]
	s_cselect_b64 s[10:11], -1, 0
	s_cmp_lg_u32 s8, 1
	v_lshl_add_u64 v[2:3], s[38:39], 0, v[132:133]
	s_cbranch_scc1 .LBB0_1410
	s_barrier
	s_setprio 1

.LBB0_1495:
	s_or_b64 exec, exec, s[6:7]
	s_mov_b64 s[6:7], s[0:1]
	v_mov_b32_e32 v8, v192
	s_waitcnt lgkmcnt(0)
	s_barrier
	s_andn2_b64 vcc, exec, s[14:15]
	v_readfirstlane_b32 s19, v8
	s_cbranch_vccnz .LBB0_1511
	v_lshlrev_b32_e32 v0, 4, v8
	v_add_u32_e32 v1, 0x2000, v0
	v_ashrrev_i32_e32 v2, 31, v1
	v_lshrrev_b32_e32 v2, 22, v2
	v_add_u32_e32 v2, v1, v2
	v_ashrrev_i32_e32 v9, 10, v2
	v_mul_i32_i24_e32 v2, 0x400, v9
	v_sub_u32_e32 v1, v1, v2
	v_lshrrev_b32_e32 v2, 4, v1
	v_bitop3_b32 v1, v2, v1, 32 bitop3:0x6c
	v_ashrrev_i32_e32 v2, 31, v1
	v_lshrrev_b32_e32 v2, 26, v2
	v_add_u32_e32 v2, v1, v2
	v_lshlrev_b32_e32 v3, 3, v9
	v_ashrrev_i32_e32 v10, 6, v2
	v_and_b32_e32 v3, -16, v3
	v_add_u32_e32 v3, v10, v3
	v_and_b32_e32 v4, 3, v10
	s_mov_b32 s8, 0xfffe0
	v_lshrrev_b32_e32 v5, 2, v3
	v_lshlrev_b32_e32 v6, 1, v3
	v_and_b32_e32 v2, 0xc0, v2
	v_and_or_b32 v4, v3, s8, v4
	v_and_b32_e32 v5, 4, v5
	v_and_b32_e32 v6, 24, v6
	v_sub_u32_e32 v1, v1, v2
	v_mov_b32_e32 v2, 1
	v_or3_b32 v4, v4, v5, v6
	v_lshlrev_b32_e32 v5, 5, v9
	v_ashrrev_i16_sdwa v1, v2, sext(v1) dst_sel:DWORD dst_unused:UNUSED_PAD src0_sel:DWORD src1_sel:BYTE_0
	v_and_b32_e32 v5, 32, v5
	v_bfe_i32 v11, v1, 0, 16
	v_add_lshl_u32 v1, v5, v11, 1
	s_waitcnt vmcnt(15)
	v_lshl_add_u32 v128, v4, 12, v1
	v_lshl_add_u32 v130, v3, 12, v1
	v_bfe_i32 v1, v8, 27, 1
	v_lshrrev_b32_e32 v1, 22, v1
	v_add_u32_e32 v1, v0, v1
	v_and_b32_e32 v1, 0xfffffc00, v1
	s_load_dwordx2 s[6:7], s[6:7], 0x80
	v_sub_u32_e32 v0, v0, v1
	v_lshrrev_b32_e32 v1, 4, v0
	v_ashrrev_i32_e32 v3, 31, v8
	v_bitop3_b32 v0, v1, v0, 32 bitop3:0x6c
	v_lshrrev_b32_e32 v3, 26, v3
	v_ashrrev_i32_e32 v1, 31, v0
	v_add_u32_e32 v3, v8, v3
	v_lshrrev_b32_e32 v1, 26, v1
	s_waitcnt vmcnt(14)
	v_ashrrev_i32_e32 v13, 6, v3
	s_waitcnt lgkmcnt(0)
	s_add_u32 s36, s6, 0x27000000
	v_add_u32_e32 v1, v0, v1
	v_lshlrev_b32_e32 v3, 3, v13
	s_addc_u32 s37, s7, 0
	v_ashrrev_i32_e32 v12, 6, v1
	v_and_b32_e32 v3, -16, v3
	s_add_u32 s38, s6, 0x8400000
	v_add_u32_e32 v3, v12, v3
	v_and_b32_e32 v4, 3, v12
	s_addc_u32 s39, s7, 0
	v_and_or_b32 v4, v3, s8, v4
	s_lshr_b32 s8, s76, 29
	s_add_i32 s8, s2, s8
	s_ashr_i32 s16, s19, 6
	s_ashr_i32 s9, s8, 3
	s_and_b32 s8, s8, -8
	s_ashr_i32 s20, s19, 8
	s_lshl_b32 s40, s16, 10
	s_sub_i32 s8, s2, s8
	s_cmp_lt_i32 s8, 0
	s_movk_i32 s41, 0xb1
	s_cselect_b32 s10, s41, 0xb0
	s_mul_i32 s8, s8, s10
	s_add_i32 s8, s8, s9
	s_mul_hi_i32 s9, s8, 0x2e8ba2e9
	s_lshr_b32 s10, s9, 31
	s_ashr_i32 s9, s9, 5
	s_add_i32 s9, s9, s10
	s_lshl_b32 s10, s9, 2
	s_mulk_i32 s9, 0xb0
	s_sub_i32 s8, s8, s9
	s_sext_i32_i16 s9, s8
	s_bfe_u32 s9, s9, 0x2001d
	s_add_i32 s9, s8, s9
	s_sext_i32_i16 s11, s9
	s_and_b32 s9, s9, 0xfffc
	s_sub_i32 s8, s8, s9
	s_sext_i32_i16 s8, s8
	v_lshrrev_b32_e32 v5, 2, v3
	v_lshlrev_b32_e32 v6, 1, v3
	v_and_b32_e32 v1, 0xc0, v1
	s_lshr_b32 s18, s11, 2
	s_add_i32 s8, s10, s8
	v_and_b32_e32 v5, 4, v5
	v_and_b32_e32 v6, 24, v6
	v_sub_u32_e32 v0, v0, v1
	s_ashr_i32 s9, s8, 31
	s_bfe_i64 s[12:13], s[18:19], 0x100000
	v_or3_b32 v4, v4, v5, v6
	v_lshlrev_b32_e32 v5, 5, v13
	v_ashrrev_i16_sdwa v0, v2, sext(v0) dst_sel:DWORD dst_unused:UNUSED_PAD src0_sel:DWORD src1_sel:BYTE_0
	s_lshl_b64 s[10:11], s[8:9], 20
	s_lshl_b64 s[12:13], s[12:13], 20
	v_and_b32_e32 v5, 32, v5
	v_bfe_i32 v14, v0, 0, 16
	s_add_u32 s30, s38, s12
	v_add_lshl_u32 v0, v5, v14, 1
	s_addc_u32 s31, s39, s13
	s_add_i32 s42, s40, 0
	v_lshl_add_u32 v132, v4, 12, v0
	s_add_i32 m0, s42, 0x10000
	v_lshl_add_u32 v134, v3, 12, v0
	global_load_lds_dwordx4 v132, s[30:31]
	s_add_i32 m0, s42, 0x12000
	s_add_u32 s12, s30, 0x80000
	global_load_lds_dwordx4 v128, s[30:31]
	s_addc_u32 s13, s31, 0
	s_add_i32 m0, s42, 0x14000
	v_mov_b32_e32 v133, 0
	global_load_lds_dwordx4 v132, s[12:13]
	s_add_i32 m0, s42, 0x16000
	s_add_u32 s28, s36, s10
	s_addc_u32 s29, s37, s11
	s_add_i32 s43, s42, 0x2000
	global_load_lds_dwordx4 v128, s[12:13]
	s_mov_b32 m0, s42
	s_add_u32 s10, s28, 0x80000
	global_load_lds_dwordx4 v134, s[28:29]
	s_mov_b32 m0, s43
	s_addc_u32 s11, s29, 0
	s_add_i32 s48, s42, 0x4000
	global_load_lds_dwordx4 v130, s[28:29]
	s_mov_b32 m0, s48
	s_add_i32 s49, s42, 0x6000
	global_load_lds_dwordx4 v134, s[10:11]
	s_mov_b32 m0, s49
	v_mov_b32_e32 v129, v133
	global_load_lds_dwordx4 v130, s[10:11]
	v_mov_b32_e32 v135, v133
	v_mov_b32_e32 v131, v133
	s_cmp_eq_u32 s20, 1
	s_mov_b32 s50, 0
	v_lshl_add_u64 v[6:7], s[30:31], 0, v[132:133]
	v_lshl_add_u64 v[4:5], s[30:31], 0, v[128:129]
	v_lshl_add_u64 v[0:1], s[28:29], 0, v[134:135]
	s_cselect_b64 s[10:11], -1, 0
	s_cmp_lg_u32 s20, 1
	v_lshl_add_u64 v[2:3], s[28:29], 0, v[130:131]
	s_cbranch_scc1 .LBB0_1498
	s_barrier
	s_setprio 1

.LBB0_1994:
	s_and_b64 vcc, exec, s[4:5]
	s_cbranch_vccnz .LBB0_2034
	v_ashrrev_i32_e32 v1, 31, v8
	v_lshrrev_b32_e32 v1, 26, v1
	v_add_u32_e32 v1, v8, v1
	v_ashrrev_i32_e32 v9, 6, v1
	v_bfe_i32 v1, v8, 27, 1
	v_lshlrev_b32_e32 v0, 4, v8
	v_lshrrev_b32_e32 v1, 22, v1
	v_add_u32_e32 v1, v0, v1
	v_and_b32_e32 v1, 0xfffffc00, v1
	v_sub_u32_e32 v1, v0, v1
	v_lshrrev_b32_e32 v2, 4, v1
	v_bitop3_b32 v1, v2, v1, 32 bitop3:0x6c
	v_ashrrev_i32_e32 v3, 31, v1
	v_lshrrev_b32_e32 v3, 26, v3
	v_lshlrev_b32_e32 v2, 3, v9
	v_add_u32_e32 v3, v1, v3
	v_and_b32_e32 v2, -16, v2
	v_ashrrev_i32_e32 v10, 6, v3
	v_and_b32_e32 v3, 0xc0, v3
	v_add_u32_e32 v2, v10, v2
	v_lshlrev_b32_e32 v4, 5, v9
	v_sub_u32_e32 v1, v1, v3
	v_mov_b32_e32 v3, 1
	v_and_b32_e32 v11, 32, v4
	v_ashrrev_i16_sdwa v1, v3, sext(v1) dst_sel:DWORD dst_unused:UNUSED_PAD src0_sel:DWORD src1_sel:BYTE_0
	v_lshlrev_b32_e32 v4, 1, v2
	v_lshrrev_b32_e32 v5, 2, v2
	v_and_b32_e32 v6, 3, v10
	s_mov_b32 s11, 0x7fffe0
	s_waitcnt vmcnt(14)
	v_bfe_i32 v12, v1, 0, 16
	v_and_b32_e32 v4, 24, v4
	v_and_b32_e32 v5, 4, v5
	v_and_or_b32 v6, v2, s11, v6
	s_movk_i32 s9, 0x1600
	v_add_u32_e32 v1, v11, v12
	v_or3_b32 v4, v6, v5, v4
	v_mul_lo_u32 v2, v2, s9
	v_add_lshl_u32 v128, v1, v2, 1
	v_mul_u32_u24_e32 v2, 0x1600, v4
	v_add_u32_e32 v0, 0x2000, v0
	v_add_lshl_u32 v130, v2, v1, 1
	v_ashrrev_i32_e32 v1, 31, v0
	v_lshrrev_b32_e32 v1, 22, v1
	v_add_u32_e32 v1, v0, v1
	v_ashrrev_i32_e32 v13, 10, v1
	v_mul_i32_i24_e32 v1, 0x400, v13
	v_sub_u32_e32 v0, v0, v1
	v_lshrrev_b32_e32 v1, 4, v0
	v_bitop3_b32 v0, v1, v0, 32 bitop3:0x6c
	v_ashrrev_i32_e32 v2, 31, v0
	v_lshrrev_b32_e32 v2, 26, v2
	s_waitcnt lgkmcnt(0)
	s_add_u32 s42, s6, 0x21800000
	v_lshlrev_b32_e32 v1, 3, v13
	v_add_u32_e32 v2, v0, v2
	s_addc_u32 s43, s7, 0
	v_and_b32_e32 v1, -16, v1
	v_ashrrev_i32_e32 v14, 6, v2
	v_lshlrev_b32_e32 v4, 5, v13
	s_add_u32 s48, s6, 0xb000000
	v_add_u32_e32 v1, v14, v1
	v_and_b32_e32 v15, 32, v4
	v_and_b32_e32 v4, 3, v14
	s_addc_u32 s49, s7, 0
	v_and_b32_e32 v2, 0xc0, v2
	v_and_or_b32 v4, v1, s11, v4
	s_ashr_i32 s11, s10, 6
	s_ashr_i32 s8, s10, 8
	v_sub_u32_e32 v0, v0, v2
	s_lshl_b32 s50, s11, 10
	s_mul_i32 s13, s65, 0x2c0000
	v_ashrrev_i16_sdwa v0, v3, sext(v0) dst_sel:DWORD dst_unused:UNUSED_PAD src0_sel:DWORD src1_sel:BYTE_0
	v_lshlrev_b32_e32 v2, 1, v1
	v_lshrrev_b32_e32 v3, 2, v1
	s_mul_hi_i32 s12, s65, 0x2c0000
	s_add_u32 s36, s48, s13
	s_waitcnt vmcnt(13)
	v_bfe_i32 v16, v0, 0, 16
	v_and_b32_e32 v2, 24, v2
	v_and_b32_e32 v3, 4, v3
	s_addc_u32 s37, s49, s12
	s_add_i32 s51, s50, 0
	v_add_u32_e32 v0, v15, v16
	v_or3_b32 v2, v4, v3, v2
	v_mul_lo_u32 v1, v1, s9
	s_add_i32 m0, s51, 0x10000
	v_add_lshl_u32 v132, v0, v1, 1
	v_mul_u32_u24_e32 v1, 0x1600, v2
	global_load_lds_dwordx4 v130, s[36:37]
	s_add_i32 m0, s51, 0x12000
	v_add_lshl_u32 v134, v1, v0, 1
	s_add_u32 s12, s36, 0x160000
	global_load_lds_dwordx4 v134, s[36:37]
	s_addc_u32 s13, s37, 0
	s_add_i32 m0, s51, 0x14000
	s_mul_i32 s15, s64, 0x2c0000
	global_load_lds_dwordx4 v130, s[12:13]
	s_add_i32 m0, s51, 0x16000
	s_mul_hi_i32 s14, s64, 0x2c0000
	s_add_u32 s34, s42, s15
	s_addc_u32 s35, s43, s14
	s_add_i32 s54, s51, 0x2000
	global_load_lds_dwordx4 v134, s[12:13]
	s_mov_b32 m0, s51
	s_add_u32 s12, s34, 0x160000
	global_load_lds_dwordx4 v128, s[34:35]
	s_mov_b32 m0, s54
	s_addc_u32 s13, s35, 0
	s_add_i32 s55, s51, 0x4000
	global_load_lds_dwordx4 v132, s[34:35]
	s_mov_b32 m0, s55
	s_add_i32 s56, s51, 0x6000
	global_load_lds_dwordx4 v128, s[12:13]
	s_mov_b32 m0, s56
	v_mov_b32_e32 v131, 0
	global_load_lds_dwordx4 v132, s[12:13]
	v_mov_b32_e32 v135, v131
	v_mov_b32_e32 v129, v131
	v_mov_b32_e32 v133, v131
	s_cmp_eq_u32 s8, 1
	s_mov_b32 s57, 0
	v_lshl_add_u64 v[6:7], s[36:37], 0, v[130:131]
	v_lshl_add_u64 v[2:3], s[36:37], 0, v[134:135]
	s_mov_b32 s22, 0x16000
	v_lshl_add_u64 v[0:1], s[34:35], 0, v[128:129]
	s_cselect_b64 s[12:13], -1, 0
	s_cmp_lg_u32 s8, 1
	v_lshl_add_u64 v[4:5], s[34:35], 0, v[132:133]
	s_cbranch_scc1 .LBB0_1997
	s_barrier
	s_setprio 1

.LBB0_2097:
	s_waitcnt vmcnt(17)
	v_ashrrev_i32_e32 v1, 31, v192
	v_lshrrev_b32_e32 v1, 26, v1
	v_add_u32_e32 v1, v192, v1
	s_waitcnt vmcnt(15)
	v_ashrrev_i32_e32 v8, 6, v1
	v_bfe_i32 v1, v192, 27, 1
	v_lshlrev_b32_e32 v0, 4, v192
	v_lshrrev_b32_e32 v1, 22, v1
	v_add_u32_e32 v1, v0, v1
	v_and_b32_e32 v1, 0xfffffc00, v1
	v_sub_u32_e32 v1, v0, v1
	v_lshrrev_b32_e32 v2, 4, v1
	v_bitop3_b32 v1, v2, v1, 32 bitop3:0x6c
	v_ashrrev_i32_e32 v3, 31, v1
	v_lshrrev_b32_e32 v3, 26, v3
	v_lshlrev_b32_e32 v2, 3, v8
	v_add_u32_e32 v3, v1, v3
	v_and_b32_e32 v2, -16, v2
	v_ashrrev_i32_e32 v9, 6, v3
	v_and_b32_e32 v3, 0xc0, v3
	v_add_u32_e32 v2, v9, v2
	v_lshlrev_b32_e32 v4, 5, v8
	v_sub_u32_e32 v1, v1, v3
	v_mov_b32_e32 v3, 1
	v_and_b32_e32 v10, 32, v4
	v_ashrrev_i16_sdwa v1, v3, sext(v1) dst_sel:DWORD dst_unused:UNUSED_PAD src0_sel:DWORD src1_sel:BYTE_0
	v_lshlrev_b32_e32 v4, 1, v2
	v_lshrrev_b32_e32 v5, 2, v2
	v_and_b32_e32 v6, 3, v9
	s_mov_b32 s12, 0x7fffe0
	v_bfe_i32 v11, v1, 0, 16
	v_and_b32_e32 v4, 24, v4
	v_and_b32_e32 v5, 4, v5
	v_and_or_b32 v6, v2, s12, v6
	s_movk_i32 s4, 0x1600
	v_add_u32_e32 v1, v10, v11
	v_or3_b32 v4, v6, v5, v4
	v_mul_lo_u32 v2, v2, s4
	v_add_lshl_u32 v128, v1, v2, 1
	v_mul_u32_u24_e32 v2, 0x1600, v4
	v_add_u32_e32 v0, 0x2000, v0
	v_add_lshl_u32 v130, v2, v1, 1
	v_ashrrev_i32_e32 v1, 31, v0
	v_lshrrev_b32_e32 v1, 22, v1
	v_add_u32_e32 v1, v0, v1
	s_waitcnt vmcnt(14)
	v_ashrrev_i32_e32 v12, 10, v1
	v_mul_i32_i24_e32 v1, 0x400, v12
	s_ashr_i32 s9, s3, 3
	v_sub_u32_e32 v0, v0, v1
	s_waitcnt lgkmcnt(0)
	s_add_u32 s3, s10, 0x21800000
	v_lshrrev_b32_e32 v1, 4, v0
	s_addc_u32 s35, s11, 0
	v_bitop3_b32 v0, v1, v0, 32 bitop3:0x6c
	s_add_u32 s36, s10, 0xb000000
	v_ashrrev_i32_e32 v2, 31, v0
	s_addc_u32 s37, s11, 0
	v_lshrrev_b32_e32 v2, 26, v2
	s_add_i32 s8, s8, s9
	v_lshlrev_b32_e32 v1, 3, v12
	v_add_u32_e32 v2, v0, v2
	s_ashr_i32 s9, s8, 31
	v_and_b32_e32 v1, -16, v1
	v_ashrrev_i32_e32 v13, 6, v2
	v_lshlrev_b32_e32 v4, 5, v12
	s_lshr_b32 s9, s9, 27
	v_add_u32_e32 v1, v13, v1
	v_and_b32_e32 v14, 32, v4
	v_and_b32_e32 v4, 3, v13
	s_add_i32 s9, s8, s9
	v_and_or_b32 v4, v1, s12, v4
	s_ashr_i32 s12, s9, 5
	s_andn2_b32 s9, s9, 31
	s_sub_i32 s8, s8, s9
	s_bfe_i32 s9, s8, 0x80000
	s_bfe_u32 s9, s9, 0x2000d
	s_add_i32 s9, s8, s9
	s_bfe_i32 s13, s9, 0x80000
	s_and_b32 s9, s9, 0xfc
	s_sub_i32 s8, s8, s9
	s_lshl_b32 s12, s12, 2
	s_sext_i32_i16 s13, s13
	s_sext_i32_i8 s8, s8
	s_ashr_i32 s5, s33, 6
	v_and_b32_e32 v2, 0xc0, v2
	s_add_i32 s34, s12, s8
	s_ashr_i32 s8, s13, 2
	s_ashr_i32 s16, s33, 8
	v_sub_u32_e32 v0, v0, v2
	s_lshl_b32 s38, s5, 10
	s_lshr_b32 s18, s13, 2
	s_mul_hi_i32 s9, s8, 0x2c0000
	s_mul_i32 s8, s8, 0x2c0000
	v_ashrrev_i16_sdwa v0, v3, sext(v0) dst_sel:DWORD dst_unused:UNUSED_PAD src0_sel:DWORD src1_sel:BYTE_0
	v_lshlrev_b32_e32 v2, 1, v1
	v_lshrrev_b32_e32 v3, 2, v1
	s_add_u32 s26, s36, s8
	v_bfe_i32 v15, v0, 0, 16
	v_and_b32_e32 v2, 24, v2
	v_and_b32_e32 v3, 4, v3
	s_addc_u32 s27, s37, s9
	s_add_i32 s39, s38, 0
	v_add_u32_e32 v0, v14, v15
	v_or3_b32 v2, v4, v3, v2
	v_mul_lo_u32 v1, v1, s4
	s_add_i32 m0, s39, 0x10000
	v_add_lshl_u32 v132, v0, v1, 1
	v_mul_u32_u24_e32 v1, 0x1600, v2
	global_load_lds_dwordx4 v130, s[26:27]
	s_add_i32 m0, s39, 0x12000
	v_add_lshl_u32 v134, v1, v0, 1
	s_add_u32 s8, s26, 0x160000
	global_load_lds_dwordx4 v134, s[26:27]
	s_addc_u32 s9, s27, 0
	s_add_i32 m0, s39, 0x14000
	s_mul_i32 s14, s34, 0x2c0000
	global_load_lds_dwordx4 v130, s[8:9]
	s_add_i32 m0, s39, 0x16000
	s_mul_hi_i32 s12, s34, 0x2c0000
	s_add_u32 s24, s3, s14
	s_addc_u32 s25, s35, s12
	s_add_i32 s40, s39, 0x2000
	global_load_lds_dwordx4 v134, s[8:9]
	s_mov_b32 m0, s39
	s_add_u32 s8, s24, 0x160000
	global_load_lds_dwordx4 v128, s[24:25]
	s_mov_b32 m0, s40
	s_addc_u32 s9, s25, 0
	s_add_i32 s41, s39, 0x4000
	global_load_lds_dwordx4 v132, s[24:25]
	s_mov_b32 m0, s41
	s_add_i32 s42, s39, 0x6000
	global_load_lds_dwordx4 v128, s[8:9]
	s_mov_b32 m0, s42
	v_mov_b32_e32 v131, 0
	global_load_lds_dwordx4 v132, s[8:9]
	s_load_dwordx2 s[8:9], s[0:1], 0x78
	s_load_dwordx2 s[12:13], s[6:7], 0x70
	v_mov_b32_e32 v135, v131
	v_mov_b32_e32 v129, v131
	v_mov_b32_e32 v133, v131
	s_cmp_eq_u32 s16, 1
	v_lshl_add_u64 v[6:7], s[26:27], 0, v[130:131]
	v_lshl_add_u64 v[2:3], s[26:27], 0, v[134:135]
	s_mov_b32 s0, 0x16000
	v_lshl_add_u64 v[0:1], s[24:25], 0, v[128:129]
	s_cselect_b64 s[14:15], -1, 0
	s_cmp_lg_u32 s16, 1
	v_lshl_add_u64 v[4:5], s[24:25], 0, v[132:133]
	s_cbranch_scc1 .LBB0_2099
	s_barrier
	s_setprio 1
